# grid barrier: acquire-invalidate issued right behind the arrival atomic (runs under its round trip / the leader's writeback)
# baseline (speedup 1.0000x reference)
; __device__ __forceinline__ unsigned xb_ld(unsigned* p)              { return __hip_atomic_load(p, __ATOMIC_RELAXED, __HIP_MEMORY_SCOPE_AGENT); }
; __device__ __forceinline__ unsigned xb_add(unsigned* p, unsigned v) { return __hip_atomic_fetch_add(p, v, __ATOMIC_RELAXED, __HIP_MEMORY_SCOPE_AGENT); }
; #define XB_SPIN(cond, bar) do { unsigned _sp = 0; while (cond) { __builtin_amdgcn_s_sleep(1); \
;     if ((++_sp & 255u) == 0u) { if (xb_ld(&(bar)[XB_TMO])) break; if (_sp > XB_SPIN_CAP) { atomicAdd(&(bar)[XB_TMO], 1u); break; } } } } while (0)
; __device__ __forceinline__ void xcd_barrier(const XcdBarrier& b) {
;     ...
;         const unsigned old = xb_add(&bar[XB_XSUB(b.x)], 1u);
;         const unsigned gen = old / nloc;
;         if (old + 1u == (gen + 1u) * nloc) {
;             __builtin_amdgcn_fence(__ATOMIC_RELEASE, "agent");
;             asm volatile("s_waitcnt vmcnt(0)" ::: "memory");
;             const unsigned og = xb_add(&bar[XB_TOP], 1u);
;             const unsigned tg = og / nx;
;             if (og + 1u == (tg + 1u) * nx) xb_add(&bar[XB_TOPGEN], 1u);
;             else XB_SPIN(xb_ld(&bar[XB_TOPGEN]) == tg, bar);
;             __builtin_amdgcn_fence(__ATOMIC_ACQUIRE, "agent");
;             xb_add(&bar[XB_XGEN(b.x)], 1u);
;             asm volatile("s_waitcnt vmcnt(0)" ::: "memory");
;         } else {
;             XB_SPIN(xb_ld(&bar[XB_XGEN(b.x)]) == gen, bar);
;             __builtin_amdgcn_fence(__ATOMIC_ACQUIRE, "agent");
;             asm volatile("s_waitcnt vmcnt(0)" ::: "memory");
;         }
.LBB0_1027:
	s_or_b64 exec, exec, s[2:3]
	buffer_inv sc1
	v_cvt_f32_u32_e32 v5, v3
	s_waitcnt vmcnt(1)
	v_readfirstlane_b32 s2, v4
	v_sub_u32_e32 v4, 0, v3
	v_rcp_iflag_f32_e32 v5, v5
	v_add_u32_e32 v6, s2, v0
	v_mul_f32_e32 v5, 0x4f7ffffe, v5
	v_cvt_u32_f32_e32 v5, v5
	v_mul_lo_u32 v0, v4, v5
	v_mul_hi_u32 v0, v5, v0
	v_add_u32_e32 v0, v5, v0
	v_mul_hi_u32 v0, v6, v0
	v_mul_lo_u32 v4, v0, v3
	v_sub_u32_e32 v4, v6, v4
	v_add_u32_e32 v5, 1, v0
	v_cmp_ge_u32_e32 vcc, v4, v3
	s_nop 1
	v_cndmask_b32_e32 v0, v0, v5, vcc
	v_sub_u32_e32 v5, v4, v3
	v_cndmask_b32_e32 v4, v4, v5, vcc
	v_add_u32_e32 v5, 1, v0
	v_cmp_ge_u32_e32 vcc, v4, v3
	v_add_u32_e32 v4, 1, v6
	s_nop 0
	v_cndmask_b32_e32 v0, v0, v5, vcc
	v_mul_lo_u32 v5, v3, v0
	v_add_u32_e32 v3, v5, v3
	v_add_u32_e32 v7, 1, v0
	v_mul_lo_u32 v7, v7, v2
	v_cmp_ne_u32_e32 vcc, v4, v3
	s_mov_b64 s[2:3], 0
	s_cbranch_vccnz .Lxb_wait
	buffer_wbl2 sc1
	s_waitcnt vmcnt(0) lgkmcnt(0)
	v_readlane_b32 s6, v251, 7
	v_readlane_b32 s7, v251, 8
	v_mov_b32_e32 v8, 1
	s_nop 3
	s_add_u32 s6, s6, 0x2200
	s_addc_u32 s7, s7, 0
	s_nop 0
	global_atomic_add v1, v8, s[6:7]
	global_atomic_add v1, v8, s[6:7] offset:256
	global_atomic_add v1, v8, s[6:7] offset:512
	global_atomic_add v1, v8, s[6:7] offset:768
	global_atomic_add v1, v8, s[6:7] offset:1024
	global_atomic_add v1, v8, s[6:7] offset:1280
	global_atomic_add v1, v8, s[6:7] offset:1536
	global_atomic_add v1, v8, s[6:7] offset:1792
	global_atomic_add v1, v8, s[6:7] offset:2048
	global_atomic_add v1, v8, s[6:7] offset:2304
	global_atomic_add v1, v8, s[6:7] offset:2560
	global_atomic_add v1, v8, s[6:7] offset:2816
	global_atomic_add v1, v8, s[6:7] offset:3072
	global_atomic_add v1, v8, s[6:7] offset:3328
	global_atomic_add v1, v8, s[6:7] offset:3584
	global_atomic_add v1, v8, s[6:7] offset:3840
.Lxb_wait:
	v_readlane_b32 s4, v252, 3
	v_readlane_b32 s5, v252, 4
	s_waitcnt lgkmcnt(0)
	s_nop 3
	global_load_dword v2, v1, s[4:5] sc1
	s_waitcnt vmcnt(0)
	v_cmp_gt_u32_e32 vcc, v7, v2
	s_and_saveexec_b64 s[4:5], vcc
	s_cbranch_execz .LBB0_1040
	s_mov_b32 s17, 1
	s_mov_b64 s[6:7], 0
	s_branch .LBB0_1031
